# XCD barrier: the second-to-last arriver of an XCD starts an asynchronous L2 write-back right after arriving (pre-flush)
# speedup vs baseline: 1.0045x; 1.0045x over previous
.LBB0_56:
	s_or_b64 exec, exec, s[10:11]
	v_cvt_f32_u32_e32 v4, v2
	s_waitcnt vmcnt(0)
	v_readfirstlane_b32 s3, v3
	v_sub_u32_e32 v3, 0, v2
	v_rcp_iflag_f32_e32 v4, v4
	v_add_u32_e32 v5, s3, v1
	v_mul_f32_e32 v4, 0x4f7ffffe, v4
	v_cvt_u32_f32_e32 v4, v4
	v_mul_lo_u32 v1, v3, v4
	v_mul_hi_u32 v1, v4, v1
	v_add_u32_e32 v1, v4, v1
	v_mul_hi_u32 v1, v5, v1
	v_mul_lo_u32 v3, v1, v2
	v_sub_u32_e32 v3, v5, v3
	v_add_u32_e32 v4, 1, v1
	v_cmp_ge_u32_e32 vcc, v3, v2
	s_nop 1
	v_cndmask_b32_e32 v1, v1, v4, vcc
	v_sub_u32_e32 v4, v3, v2
	v_cndmask_b32_e32 v3, v3, v4, vcc
	v_add_u32_e32 v4, 1, v1
	v_cmp_ge_u32_e32 vcc, v3, v2
	v_add_u32_e32 v3, 1, v5
	s_nop 0
	v_cndmask_b32_e32 v1, v1, v4, vcc
	v_mul_lo_u32 v4, v2, v1
	v_add_u32_e32 v2, v4, v2
	v_cmp_ne_u32_e32 vcc, v3, v2
	s_and_saveexec_b64 s[8:9], vcc
	s_xor_b64 s[8:9], exec, s[8:9]
	s_cbranch_execz .LBB0_70
	s_waitcnt lgkmcnt(0)
	v_mov_b32_e32 v0, 0x2000
	v_add_u32_e32 v4, 1, v3
	v_cmp_eq_u32_e32 vcc, v4, v2
	s_cbranch_vccz .Lpf_11
	buffer_wbl2 sc1
.Lpf_11:
	buffer_inv sc1
	global_load_dword v0, v0, s[6:7] offset:1024 sc1
	s_add_u32 s14, s6, 0x2400
	s_addc_u32 s15, s7, 0
	s_waitcnt vmcnt(0)
	v_cmp_eq_u32_e32 vcc, v0, v1
	s_and_saveexec_b64 s[10:11], vcc
	s_cbranch_execz .LBB0_69
	s_add_u32 s12, s4, 0x11080200
	s_addc_u32 s13, s5, 0
	s_mov_b32 s3, 1
	s_mov_b64 s[16:17], 0
	v_mov_b32_e32 v0, 0
	s_branch .LBB0_60

.LBB0_600:
	s_or_b64 exec, exec, s[14:15]
	v_cvt_f32_u32_e32 v4, v2
	s_waitcnt vmcnt(0)
	v_readfirstlane_b32 s0, v3
	v_sub_u32_e32 v3, 0, v2
	v_rcp_iflag_f32_e32 v4, v4
	v_add_u32_e32 v5, s0, v1
	v_mul_f32_e32 v4, 0x4f7ffffe, v4
	v_cvt_u32_f32_e32 v4, v4
	v_mul_lo_u32 v1, v3, v4
	v_mul_hi_u32 v1, v4, v1
	v_add_u32_e32 v1, v4, v1
	v_mul_hi_u32 v1, v5, v1
	v_mul_lo_u32 v3, v1, v2
	v_sub_u32_e32 v3, v5, v3
	v_add_u32_e32 v4, 1, v1
	v_cmp_ge_u32_e32 vcc, v3, v2
	s_nop 1
	v_cndmask_b32_e32 v1, v1, v4, vcc
	v_sub_u32_e32 v4, v3, v2
	v_cndmask_b32_e32 v3, v3, v4, vcc
	v_add_u32_e32 v4, 1, v1
	v_cmp_ge_u32_e32 vcc, v3, v2
	v_add_u32_e32 v3, 1, v5
	s_nop 0
	v_cndmask_b32_e32 v1, v1, v4, vcc
	v_mul_lo_u32 v4, v2, v1
	v_add_u32_e32 v2, v4, v2
	v_cmp_ne_u32_e32 vcc, v3, v2
	s_and_saveexec_b64 s[0:1], vcc
	s_xor_b64 s[12:13], exec, s[0:1]
	s_cbranch_execz .LBB0_614
	s_waitcnt lgkmcnt(0)
	v_add_u32_e32 v4, 1, v3
	v_cmp_eq_u32_e32 vcc, v4, v2
	s_cbranch_vccz .Lpf_7
	buffer_wbl2 sc1
.Lpf_7:
	buffer_inv sc1
	global_load_dword v0, v218, s[10:11] offset:1024 sc1
	s_add_u32 s18, s10, 0x2400
	s_addc_u32 s19, s11, 0
	s_waitcnt vmcnt(0)
	v_cmp_eq_u32_e32 vcc, v0, v1
	s_and_saveexec_b64 s[14:15], vcc
	s_cbranch_execz .LBB0_613
	s_add_u32 s16, s8, 0x11080200
	s_addc_u32 s17, s9, 0
	s_mov_b32 s0, 1
	s_mov_b64 s[20:21], 0
	s_branch .LBB0_604

.LBB0_1275:
	s_or_b64 exec, exec, s[18:19]
	v_cvt_f32_u32_e32 v4, v2
	s_waitcnt vmcnt(0)
	v_readfirstlane_b32 s0, v3
	v_sub_u32_e32 v3, 0, v2
	v_rcp_iflag_f32_e32 v4, v4
	v_add_u32_e32 v5, s0, v1
	v_mul_f32_e32 v4, 0x4f7ffffe, v4
	v_cvt_u32_f32_e32 v4, v4
	v_mul_lo_u32 v1, v3, v4
	v_mul_hi_u32 v1, v4, v1
	v_add_u32_e32 v1, v4, v1
	v_mul_hi_u32 v1, v5, v1
	v_mul_lo_u32 v3, v1, v2
	v_sub_u32_e32 v3, v5, v3
	v_add_u32_e32 v4, 1, v1
	v_cmp_ge_u32_e32 vcc, v3, v2
	s_nop 1
	v_cndmask_b32_e32 v1, v1, v4, vcc
	v_sub_u32_e32 v4, v3, v2
	v_cndmask_b32_e32 v3, v3, v4, vcc
	v_add_u32_e32 v4, 1, v1
	v_cmp_ge_u32_e32 vcc, v3, v2
	v_add_u32_e32 v3, 1, v5
	s_nop 0
	v_cndmask_b32_e32 v1, v1, v4, vcc
	v_mul_lo_u32 v4, v2, v1
	v_add_u32_e32 v2, v4, v2
	v_cmp_ne_u32_e32 vcc, v3, v2
	s_and_saveexec_b64 s[0:1], vcc
	s_xor_b64 s[16:17], exec, s[0:1]
	s_cbranch_execz .LBB0_1289
	s_waitcnt lgkmcnt(0)
	v_add_u32_e32 v4, 1, v3
	v_cmp_eq_u32_e32 vcc, v4, v2
	s_cbranch_vccz .Lpf_1
	buffer_wbl2 sc1
.Lpf_1:
	buffer_inv sc1
	global_load_dword v0, v218, s[14:15] offset:1024 sc1
	s_add_u32 s22, s14, 0x2400
	s_addc_u32 s23, s15, 0
	s_waitcnt vmcnt(0)
	v_cmp_eq_u32_e32 vcc, v0, v1
	s_and_saveexec_b64 s[18:19], vcc
	s_cbranch_execz .LBB0_1288
	s_add_u32 s20, s12, 0x11080200
	s_addc_u32 s21, s13, 0
	s_mov_b32 s0, 1
	s_mov_b64 s[24:25], 0
	s_branch .LBB0_1279
